# attention key loop emitted once per wave half: half-step priorities as s_setprio immediates, the two priority-selection branch sequences per iteration removed; body otherwise identical
# speedup vs baseline: 1.0208x; 1.0005x over previous
.Lan_entry:
	v_cvt_f32_i32_e32 v255, v231
	v_add_f32_e32 v255, 0x42800000, v255
	v_cmp_eq_u32_e32 vcc, 0, v203
	s_nop 1
	v_cndmask_b32_e32 v208, v229, v255, vcc
	v_add_f32_e32 v255, 0x80000000, v208
	v_fma_f32 v96, -v201, |v255|, v253
	v_add_f32_e32 v255, 0xbf800000, v208
	v_fma_f32 v97, -v201, |v255|, v253
	v_add_f32_e32 v255, 0xc0000000, v208
	v_fma_f32 v98, -v201, |v255|, v253
	v_add_f32_e32 v255, 0xc0400000, v208
	v_fma_f32 v99, -v201, |v255|, v253
	v_add_f32_e32 v255, 0xc0800000, v208
	v_fma_f32 v100, -v201, |v255|, v253
	v_add_f32_e32 v255, 0xc0a00000, v208
	v_fma_f32 v101, -v201, |v255|, v253
	v_add_f32_e32 v255, 0xc0c00000, v208
	v_fma_f32 v102, -v201, |v255|, v253
	v_add_f32_e32 v255, 0xc0e00000, v208
	v_fma_f32 v103, -v201, |v255|, v253
	v_add_f32_e32 v255, 0xc1800000, v208
	v_fma_f32 v104, -v201, |v255|, v253
	v_add_f32_e32 v255, 0xc1880000, v208
	v_fma_f32 v105, -v201, |v255|, v253
	v_add_f32_e32 v255, 0xc1900000, v208
	v_fma_f32 v106, -v201, |v255|, v253
	v_add_f32_e32 v255, 0xc1980000, v208
	v_fma_f32 v107, -v201, |v255|, v253
	v_add_f32_e32 v255, 0xc1a00000, v208
	v_fma_f32 v108, -v201, |v255|, v253
	v_add_f32_e32 v255, 0xc1a80000, v208
	v_fma_f32 v109, -v201, |v255|, v253
	v_add_f32_e32 v255, 0xc1b00000, v208
	v_fma_f32 v110, -v201, |v255|, v253
	v_add_f32_e32 v255, 0xc1b80000, v208
	v_fma_f32 v111, -v201, |v255|, v253
	v_mov_b32_e32 v80, 0xff61b1e6
	v_mov_b32_e32 v81, 0xff61b1e6
	v_mov_b32_e32 v82, 0xff61b1e6
	v_mov_b32_e32 v83, 0xff61b1e6
	v_mov_b32_e32 v84, 0xff61b1e6
	v_mov_b32_e32 v85, 0xff61b1e6
	v_mov_b32_e32 v86, 0xff61b1e6
	v_mov_b32_e32 v87, 0xff61b1e6
	v_mov_b32_e32 v88, 0xff61b1e6
	v_mov_b32_e32 v89, 0xff61b1e6
	v_mov_b32_e32 v90, 0xff61b1e6
	v_mov_b32_e32 v91, 0xff61b1e6
	v_mov_b32_e32 v92, 0xff61b1e6
	v_mov_b32_e32 v93, 0xff61b1e6
	v_mov_b32_e32 v94, 0xff61b1e6
	v_mov_b32_e32 v95, 0xff61b1e6
	s_cmp_eq_u32 s85, 1
	s_cbranch_scc1 .Lan_327_h1

.Lan_331_h0:
	v_cvt_f32_i32_e32 v237, v231
	v_xor_b32_e32 v236, 0x80000000, v201
	s_setprio 1
	s_waitcnt lgkmcnt(4)
	v_mfma_f32_32x32x16_bf16 v[96:111], v[64:67], v[112:115], v[96:111]
	ds_read_b128 v[244:247], v234 offset:34848
	v_exp_f32_e32 v80, v80
	v_exp_f32_e32 v81, v81
	v_add_f32_e32 v238, 0, v80
	v_add_f32_e32 v238, v238, v81
	s_waitcnt lgkmcnt(4)
	v_mfma_f32_32x32x16_bf16 v[96:111], v[68:71], v[116:119], v[96:111]
	ds_read_b128 v[64:67], v234 offset:39424
	v_exp_f32_e32 v82, v82
	v_exp_f32_e32 v83, v83
	v_add_f32_e32 v238, v238, v82
	v_add_f32_e32 v238, v238, v83
	s_waitcnt lgkmcnt(4)
	v_mfma_f32_32x32x16_bf16 v[96:111], v[72:75], v[120:123], v[96:111]
	ds_read_b128 v[68:71], v234 offset:39456
	v_exp_f32_e32 v84, v84
	v_exp_f32_e32 v85, v85
	v_add_f32_e32 v238, v238, v84
	v_add_f32_e32 v238, v238, v85
	s_waitcnt lgkmcnt(4)
	v_mfma_f32_32x32x16_bf16 v[96:111], v[76:79], v[124:127], v[96:111]
	ds_read_b128 v[72:75], v234 offset:44032
	v_exp_f32_e32 v86, v86
	v_exp_f32_e32 v87, v87
	v_add_f32_e32 v238, v238, v86
	v_add_f32_e32 v238, v238, v87
	s_waitcnt lgkmcnt(4)
	v_mfma_f32_32x32x16_bf16 v[48:63], v[160:163], v[144:147], v[48:63]
	ds_read_b128 v[76:79], v234 offset:44064
	v_cvt_pk_bf16_f32 v152, v80, v81
	v_cvt_pk_bf16_f32 v153, v82, v83
	v_cvt_pk_bf16_f32 v154, v84, v85
	v_cvt_pk_bf16_f32 v155, v86, v87
	v_add_f32_e32 v255, 0x42800000, v237
	v_fma_f32 v254, v236, v255, v253
	s_waitcnt lgkmcnt(4)
	v_mfma_f32_32x32x16_bf16 v[48:63], v[244:247], v[148:151], v[48:63]
	ds_read_b128 v[160:163], v234 offset:48640
	v_exp_f32_e32 v88, v88
	v_exp_f32_e32 v89, v89
	v_add_f32_e32 v238, v238, v88
	v_add_f32_e32 v238, v238, v89
	v_fmamk_f32 v80, v201, 0x42000000, v254
	v_fmamk_f32 v81, v201, 0x42040000, v254
	s_waitcnt lgkmcnt(4)
	v_mfma_f32_32x32x16_bf16 v[32:47], v[64:67], v[144:147], v[32:47]
	ds_read_b128 v[244:247], v234 offset:48672
	v_exp_f32_e32 v90, v90
	v_exp_f32_e32 v91, v91
	v_add_f32_e32 v238, v238, v90
	v_add_f32_e32 v238, v238, v91
	v_fmamk_f32 v82, v201, 0x42080000, v254
	v_fmamk_f32 v83, v201, 0x420c0000, v254
	s_waitcnt lgkmcnt(4)
	v_mfma_f32_32x32x16_bf16 v[32:47], v[68:71], v[148:151], v[32:47]
	ds_read_b128 v[64:67], v235 offset:8704
	v_exp_f32_e32 v92, v92
	v_exp_f32_e32 v93, v93
	v_add_f32_e32 v238, v238, v92
	v_add_f32_e32 v238, v238, v93
	v_fmamk_f32 v84, v201, 0x42100000, v254
	v_fmamk_f32 v85, v201, 0x42140000, v254
	s_waitcnt lgkmcnt(4)
	v_mfma_f32_32x32x16_bf16 v[16:31], v[72:75], v[144:147], v[16:31]
	ds_read_b128 v[68:71], v235 offset:8736
	v_exp_f32_e32 v94, v94
	v_exp_f32_e32 v95, v95
	v_add_f32_e32 v238, v238, v94
	v_add_f32_e32 v238, v238, v95
	v_fmamk_f32 v86, v201, 0x42180000, v254
	v_fmamk_f32 v87, v201, 0x421c0000, v254
	s_waitcnt lgkmcnt(4)
	v_mfma_f32_32x32x16_bf16 v[16:31], v[76:79], v[148:151], v[16:31]
	ds_read_b128 v[72:75], v235 offset:8768
	v_cvt_pk_bf16_f32 v156, v88, v89
	v_cvt_pk_bf16_f32 v157, v90, v91
	v_cvt_pk_bf16_f32 v158, v92, v93
	v_cvt_pk_bf16_f32 v159, v94, v95
	s_waitcnt lgkmcnt(4)
	v_mfma_f32_32x32x16_bf16 v[0:15], v[160:163], v[144:147], v[0:15]
	ds_read_b128 v[76:79], v235 offset:8800
	v_fmamk_f32 v88, v201, 0x42400000, v254
	v_fmamk_f32 v89, v201, 0x42440000, v254
	v_fmamk_f32 v90, v201, 0x42480000, v254
	v_fmamk_f32 v91, v201, 0x424c0000, v254
	v_add_f32_e32 v238, v238, v233
	s_waitcnt lgkmcnt(4)
	v_mfma_f32_32x32x16_bf16 v[0:15], v[244:247], v[148:151], v[0:15]
	ds_read_b128 v[160:163], v234 offset:34880
	v_fmamk_f32 v92, v201, 0x42500000, v254
	v_fmamk_f32 v93, v201, 0x42540000, v254
	v_fmamk_f32 v94, v201, 0x42580000, v254
	v_fmamk_f32 v95, v201, 0x425c0000, v254
	s_cmp_lt_u32 s90, 2
	s_cbranch_scc1 .LfixA_skip_h0_do
	s_cmp_lt_i32 s90, s38
	s_cbranch_scc1 .LfixA_skip_h0

.LfixA_skip_h0:
	s_setprio 0
	s_waitcnt lgkmcnt(4)
	v_mfma_f32_32x32x16_bf16 v[80:95], v[64:67], v[112:115], v[80:95]
	ds_read_b128 v[244:247], v234 offset:34912
	v_exp_f32_e32 v96, v96
	v_exp_f32_e32 v97, v97
	v_add_f32_e32 v233, 0, v96
	v_add_f32_e32 v233, v233, v97
	s_waitcnt lgkmcnt(4)
	v_mfma_f32_32x32x16_bf16 v[80:95], v[68:71], v[116:119], v[80:95]
	ds_read_b128 v[64:67], v234 offset:39488
	v_exp_f32_e32 v98, v98
	v_exp_f32_e32 v99, v99
	v_add_f32_e32 v233, v233, v98
	v_add_f32_e32 v233, v233, v99
	s_waitcnt lgkmcnt(4)
	v_mfma_f32_32x32x16_bf16 v[80:95], v[72:75], v[120:123], v[80:95]
	ds_read_b128 v[68:71], v234 offset:39520
	v_exp_f32_e32 v100, v100
	v_exp_f32_e32 v101, v101
	v_add_f32_e32 v233, v233, v100
	v_add_f32_e32 v233, v233, v101
	s_waitcnt lgkmcnt(4)
	v_mfma_f32_32x32x16_bf16 v[80:95], v[76:79], v[124:127], v[80:95]
	ds_read_b128 v[72:75], v234 offset:44096
	v_exp_f32_e32 v102, v102
	v_exp_f32_e32 v103, v103
	v_add_f32_e32 v233, v233, v102
	v_add_f32_e32 v233, v233, v103
	s_waitcnt lgkmcnt(4)
	v_mfma_f32_32x32x16_bf16 v[48:63], v[160:163], v[152:155], v[48:63]
	ds_read_b128 v[76:79], v234 offset:44128
	v_cvt_pk_bf16_f32 v144, v96, v97
	v_cvt_pk_bf16_f32 v145, v98, v99
	v_cvt_pk_bf16_f32 v146, v100, v101
	v_cvt_pk_bf16_f32 v147, v102, v103
	v_add_f32_e32 v255, 0x43000000, v237
	v_fma_f32 v254, v236, v255, v253
	s_waitcnt lgkmcnt(4)
	v_mfma_f32_32x32x16_bf16 v[48:63], v[244:247], v[156:159], v[48:63]
	ds_read_b128 v[160:163], v234 offset:48704
	v_exp_f32_e32 v104, v104
	v_exp_f32_e32 v105, v105
	v_add_f32_e32 v233, v233, v104
	v_add_f32_e32 v233, v233, v105
	v_fmamk_f32 v96, v201, 0x00000000, v254
	v_fmamk_f32 v97, v201, 0x3f800000, v254
	s_waitcnt lgkmcnt(4)
	v_mfma_f32_32x32x16_bf16 v[32:47], v[64:67], v[152:155], v[32:47]
	ds_read_b128 v[244:247], v234 offset:48736
	v_exp_f32_e32 v106, v106
	v_exp_f32_e32 v107, v107
	v_add_f32_e32 v233, v233, v106
	v_add_f32_e32 v233, v233, v107
	v_fmamk_f32 v98, v201, 0x40000000, v254
	v_fmamk_f32 v99, v201, 0x40400000, v254
	s_waitcnt lgkmcnt(4)
	v_mfma_f32_32x32x16_bf16 v[32:47], v[68:71], v[156:159], v[32:47]
	v_exp_f32_e32 v108, v108
	v_exp_f32_e32 v109, v109
	v_add_f32_e32 v233, v233, v108
	v_add_f32_e32 v233, v233, v109
	v_fmamk_f32 v100, v201, 0x40800000, v254
	v_fmamk_f32 v101, v201, 0x40a00000, v254
	s_waitcnt lgkmcnt(3)
	v_mfma_f32_32x32x16_bf16 v[16:31], v[72:75], v[152:155], v[16:31]
	v_exp_f32_e32 v110, v110
	v_exp_f32_e32 v111, v111
	v_add_f32_e32 v233, v233, v110
	v_add_f32_e32 v233, v233, v111
	v_fmamk_f32 v102, v201, 0x40c00000, v254
	v_fmamk_f32 v103, v201, 0x40e00000, v254
	s_waitcnt lgkmcnt(2)
	v_mfma_f32_32x32x16_bf16 v[16:31], v[76:79], v[156:159], v[16:31]
	v_cvt_pk_bf16_f32 v148, v104, v105
	v_cvt_pk_bf16_f32 v149, v106, v107
	v_cvt_pk_bf16_f32 v150, v108, v109
	v_cvt_pk_bf16_f32 v151, v110, v111
	s_waitcnt lgkmcnt(1)
	v_mfma_f32_32x32x16_bf16 v[0:15], v[160:163], v[152:155], v[0:15]
	v_fmamk_f32 v104, v201, 0x41800000, v254
	v_fmamk_f32 v105, v201, 0x41880000, v254
	v_fmamk_f32 v106, v201, 0x41900000, v254
	v_fmamk_f32 v107, v201, 0x41980000, v254
	v_add_f32_e32 v233, v233, v238
	s_waitcnt lgkmcnt(0)
	v_mfma_f32_32x32x16_bf16 v[0:15], v[244:247], v[156:159], v[0:15]
	v_fmamk_f32 v108, v201, 0x41a00000, v254
	v_fmamk_f32 v109, v201, 0x41a80000, v254
	v_fmamk_f32 v110, v201, 0x41b00000, v254
	v_fmamk_f32 v111, v201, 0x41b80000, v254
	s_cmp_lt_u32 s90, 1
	s_cbranch_scc1 .LfixB_skip_h0_do
	s_cmp_lt_i32 s87, s38
	s_cbranch_scc1 .LfixB_skip_h0

.Lan_345_h0:
	v_lshl_add_u64 v[204:205], v[204:205], 0, s[30:31]
	v_lshl_add_u64 v[206:207], v[206:207], 0, s[44:45]
	s_cmp_eq_u32 s86, s87
	v_add_u32_e32 v231, 64, v231
	s_waitcnt lgkmcnt(0)
	s_barrier
	s_cbranch_scc1 .LBB0_347
	s_mov_b32 s90, s87
	s_branch .Lan_327_h0
.Lan_327_h1:
	s_and_b32 s88, s90, 1
	s_mul_i32 s33, s88, 0x4400
	v_add_u32_e32 v235, s33, v230
	s_add_i32 s87, s90, 1
	s_and_b32 s89, s87, 1
	s_mul_i32 s33, s89, 0x4800
	v_add_u32_e32 v234, s33, v215
	ds_read_b128 v[64:67], v235
	ds_read_b128 v[68:71], v235 offset:32
	ds_read_b128 v[72:75], v235 offset:64
	ds_read_b128 v[76:79], v235 offset:96
	ds_read_b128 v[160:163], v234 offset:34816
	s_cmp_lt_i32 s87, s38
	s_cselect_b64 s[54:55], -1, 0
	s_cmp_ge_i32 s87, s38
	s_cbranch_scc1 .Lan_329_h1
	v_lshl_add_u64 v[244:245], s[62:63], 0, v[206:207]
	v_add_co_u32_e32 v246, vcc, 0x8f61000, v244
	s_nop 1
	v_addc_co_u32_e32 v247, vcc, 0, v245, vcc
	v_add_co_u32_e32 v244, vcc, 0x8f89000, v244
	s_nop 1
	v_addc_co_u32_e32 v245, vcc, 0, v245, vcc
	global_load_dwordx4 v[128:131], v[246:247], off
	global_load_dwordx4 v[132:135], v[244:245], off

.Lan_331_h1:
	v_cvt_f32_i32_e32 v237, v231
	v_xor_b32_e32 v236, 0x80000000, v201
	s_setprio 0
	s_waitcnt lgkmcnt(4)
	v_mfma_f32_32x32x16_bf16 v[96:111], v[64:67], v[112:115], v[96:111]
	ds_read_b128 v[244:247], v234 offset:34848
	v_exp_f32_e32 v80, v80
	v_exp_f32_e32 v81, v81
	v_add_f32_e32 v238, 0, v80
	v_add_f32_e32 v238, v238, v81
	s_waitcnt lgkmcnt(4)
	v_mfma_f32_32x32x16_bf16 v[96:111], v[68:71], v[116:119], v[96:111]
	ds_read_b128 v[64:67], v234 offset:39424
	v_exp_f32_e32 v82, v82
	v_exp_f32_e32 v83, v83
	v_add_f32_e32 v238, v238, v82
	v_add_f32_e32 v238, v238, v83
	s_waitcnt lgkmcnt(4)
	v_mfma_f32_32x32x16_bf16 v[96:111], v[72:75], v[120:123], v[96:111]
	ds_read_b128 v[68:71], v234 offset:39456
	v_exp_f32_e32 v84, v84
	v_exp_f32_e32 v85, v85
	v_add_f32_e32 v238, v238, v84
	v_add_f32_e32 v238, v238, v85
	s_waitcnt lgkmcnt(4)
	v_mfma_f32_32x32x16_bf16 v[96:111], v[76:79], v[124:127], v[96:111]
	ds_read_b128 v[72:75], v234 offset:44032
	v_exp_f32_e32 v86, v86
	v_exp_f32_e32 v87, v87
	v_add_f32_e32 v238, v238, v86
	v_add_f32_e32 v238, v238, v87
	s_waitcnt lgkmcnt(4)
	v_mfma_f32_32x32x16_bf16 v[48:63], v[160:163], v[144:147], v[48:63]
	ds_read_b128 v[76:79], v234 offset:44064
	v_cvt_pk_bf16_f32 v152, v80, v81
	v_cvt_pk_bf16_f32 v153, v82, v83
	v_cvt_pk_bf16_f32 v154, v84, v85
	v_cvt_pk_bf16_f32 v155, v86, v87
	v_add_f32_e32 v255, 0x42800000, v237
	v_fma_f32 v254, v236, v255, v253
	s_waitcnt lgkmcnt(4)
	v_mfma_f32_32x32x16_bf16 v[48:63], v[244:247], v[148:151], v[48:63]
	ds_read_b128 v[160:163], v234 offset:48640
	v_exp_f32_e32 v88, v88
	v_exp_f32_e32 v89, v89
	v_add_f32_e32 v238, v238, v88
	v_add_f32_e32 v238, v238, v89
	v_fmamk_f32 v80, v201, 0x42000000, v254
	v_fmamk_f32 v81, v201, 0x42040000, v254
	s_waitcnt lgkmcnt(4)
	v_mfma_f32_32x32x16_bf16 v[32:47], v[64:67], v[144:147], v[32:47]
	ds_read_b128 v[244:247], v234 offset:48672
	v_exp_f32_e32 v90, v90
	v_exp_f32_e32 v91, v91
	v_add_f32_e32 v238, v238, v90
	v_add_f32_e32 v238, v238, v91
	v_fmamk_f32 v82, v201, 0x42080000, v254
	v_fmamk_f32 v83, v201, 0x420c0000, v254
	s_waitcnt lgkmcnt(4)
	v_mfma_f32_32x32x16_bf16 v[32:47], v[68:71], v[148:151], v[32:47]
	ds_read_b128 v[64:67], v235 offset:8704
	v_exp_f32_e32 v92, v92
	v_exp_f32_e32 v93, v93
	v_add_f32_e32 v238, v238, v92
	v_add_f32_e32 v238, v238, v93
	v_fmamk_f32 v84, v201, 0x42100000, v254
	v_fmamk_f32 v85, v201, 0x42140000, v254
	s_waitcnt lgkmcnt(4)
	v_mfma_f32_32x32x16_bf16 v[16:31], v[72:75], v[144:147], v[16:31]
	ds_read_b128 v[68:71], v235 offset:8736
	v_exp_f32_e32 v94, v94
	v_exp_f32_e32 v95, v95
	v_add_f32_e32 v238, v238, v94
	v_add_f32_e32 v238, v238, v95
	v_fmamk_f32 v86, v201, 0x42180000, v254
	v_fmamk_f32 v87, v201, 0x421c0000, v254
	s_waitcnt lgkmcnt(4)
	v_mfma_f32_32x32x16_bf16 v[16:31], v[76:79], v[148:151], v[16:31]
	ds_read_b128 v[72:75], v235 offset:8768
	v_cvt_pk_bf16_f32 v156, v88, v89
	v_cvt_pk_bf16_f32 v157, v90, v91
	v_cvt_pk_bf16_f32 v158, v92, v93
	v_cvt_pk_bf16_f32 v159, v94, v95
	s_waitcnt lgkmcnt(4)
	v_mfma_f32_32x32x16_bf16 v[0:15], v[160:163], v[144:147], v[0:15]
	ds_read_b128 v[76:79], v235 offset:8800
	v_fmamk_f32 v88, v201, 0x42400000, v254
	v_fmamk_f32 v89, v201, 0x42440000, v254
	v_fmamk_f32 v90, v201, 0x42480000, v254
	v_fmamk_f32 v91, v201, 0x424c0000, v254
	v_add_f32_e32 v238, v238, v233
	s_waitcnt lgkmcnt(4)
	v_mfma_f32_32x32x16_bf16 v[0:15], v[244:247], v[148:151], v[0:15]
	ds_read_b128 v[160:163], v234 offset:34880
	v_fmamk_f32 v92, v201, 0x42500000, v254
	v_fmamk_f32 v93, v201, 0x42540000, v254
	v_fmamk_f32 v94, v201, 0x42580000, v254
	v_fmamk_f32 v95, v201, 0x425c0000, v254
	s_cmp_lt_u32 s90, 2
	s_cbranch_scc1 .LfixA_skip_h1_do
	s_cmp_lt_i32 s90, s38
	s_cbranch_scc1 .LfixA_skip_h1

.LfixA_skip_h1:
	s_setprio 1
	s_waitcnt lgkmcnt(4)
	v_mfma_f32_32x32x16_bf16 v[80:95], v[64:67], v[112:115], v[80:95]
	ds_read_b128 v[244:247], v234 offset:34912
	v_exp_f32_e32 v96, v96
	v_exp_f32_e32 v97, v97
	v_add_f32_e32 v233, 0, v96
	v_add_f32_e32 v233, v233, v97
	s_waitcnt lgkmcnt(4)
	v_mfma_f32_32x32x16_bf16 v[80:95], v[68:71], v[116:119], v[80:95]
	ds_read_b128 v[64:67], v234 offset:39488
	v_exp_f32_e32 v98, v98
	v_exp_f32_e32 v99, v99
	v_add_f32_e32 v233, v233, v98
	v_add_f32_e32 v233, v233, v99
	s_waitcnt lgkmcnt(4)
	v_mfma_f32_32x32x16_bf16 v[80:95], v[72:75], v[120:123], v[80:95]
	ds_read_b128 v[68:71], v234 offset:39520
	v_exp_f32_e32 v100, v100
	v_exp_f32_e32 v101, v101
	v_add_f32_e32 v233, v233, v100
	v_add_f32_e32 v233, v233, v101
	s_waitcnt lgkmcnt(4)
	v_mfma_f32_32x32x16_bf16 v[80:95], v[76:79], v[124:127], v[80:95]
	ds_read_b128 v[72:75], v234 offset:44096
	v_exp_f32_e32 v102, v102
	v_exp_f32_e32 v103, v103
	v_add_f32_e32 v233, v233, v102
	v_add_f32_e32 v233, v233, v103
	s_waitcnt lgkmcnt(4)
	v_mfma_f32_32x32x16_bf16 v[48:63], v[160:163], v[152:155], v[48:63]
	ds_read_b128 v[76:79], v234 offset:44128
	v_cvt_pk_bf16_f32 v144, v96, v97
	v_cvt_pk_bf16_f32 v145, v98, v99
	v_cvt_pk_bf16_f32 v146, v100, v101
	v_cvt_pk_bf16_f32 v147, v102, v103
	v_add_f32_e32 v255, 0x43000000, v237
	v_fma_f32 v254, v236, v255, v253
	s_waitcnt lgkmcnt(4)
	v_mfma_f32_32x32x16_bf16 v[48:63], v[244:247], v[156:159], v[48:63]
	ds_read_b128 v[160:163], v234 offset:48704
	v_exp_f32_e32 v104, v104
	v_exp_f32_e32 v105, v105
	v_add_f32_e32 v233, v233, v104
	v_add_f32_e32 v233, v233, v105
	v_fmamk_f32 v96, v201, 0x00000000, v254
	v_fmamk_f32 v97, v201, 0x3f800000, v254
	s_waitcnt lgkmcnt(4)
	v_mfma_f32_32x32x16_bf16 v[32:47], v[64:67], v[152:155], v[32:47]
	ds_read_b128 v[244:247], v234 offset:48736
	v_exp_f32_e32 v106, v106
	v_exp_f32_e32 v107, v107
	v_add_f32_e32 v233, v233, v106
	v_add_f32_e32 v233, v233, v107
	v_fmamk_f32 v98, v201, 0x40000000, v254
	v_fmamk_f32 v99, v201, 0x40400000, v254
	s_waitcnt lgkmcnt(4)
	v_mfma_f32_32x32x16_bf16 v[32:47], v[68:71], v[156:159], v[32:47]
	v_exp_f32_e32 v108, v108
	v_exp_f32_e32 v109, v109
	v_add_f32_e32 v233, v233, v108
	v_add_f32_e32 v233, v233, v109
	v_fmamk_f32 v100, v201, 0x40800000, v254
	v_fmamk_f32 v101, v201, 0x40a00000, v254
	s_waitcnt lgkmcnt(3)
	v_mfma_f32_32x32x16_bf16 v[16:31], v[72:75], v[152:155], v[16:31]
	v_exp_f32_e32 v110, v110
	v_exp_f32_e32 v111, v111
	v_add_f32_e32 v233, v233, v110
	v_add_f32_e32 v233, v233, v111
	v_fmamk_f32 v102, v201, 0x40c00000, v254
	v_fmamk_f32 v103, v201, 0x40e00000, v254
	s_waitcnt lgkmcnt(2)
	v_mfma_f32_32x32x16_bf16 v[16:31], v[76:79], v[156:159], v[16:31]
	v_cvt_pk_bf16_f32 v148, v104, v105
	v_cvt_pk_bf16_f32 v149, v106, v107
	v_cvt_pk_bf16_f32 v150, v108, v109
	v_cvt_pk_bf16_f32 v151, v110, v111
	s_waitcnt lgkmcnt(1)
	v_mfma_f32_32x32x16_bf16 v[0:15], v[160:163], v[152:155], v[0:15]
	v_fmamk_f32 v104, v201, 0x41800000, v254
	v_fmamk_f32 v105, v201, 0x41880000, v254
	v_fmamk_f32 v106, v201, 0x41900000, v254
	v_fmamk_f32 v107, v201, 0x41980000, v254
	v_add_f32_e32 v233, v233, v238
	s_waitcnt lgkmcnt(0)
	v_mfma_f32_32x32x16_bf16 v[0:15], v[244:247], v[156:159], v[0:15]
	v_fmamk_f32 v108, v201, 0x41a00000, v254
	v_fmamk_f32 v109, v201, 0x41a80000, v254
	v_fmamk_f32 v110, v201, 0x41b00000, v254
	v_fmamk_f32 v111, v201, 0x41b80000, v254
	s_cmp_lt_u32 s90, 1
	s_cbranch_scc1 .LfixB_skip_h1_do
	s_cmp_lt_i32 s87, s38
	s_cbranch_scc1 .LfixB_skip_h1
